# barriers: each workgroup's agent-scope L1 invalidate is issued behind its arrival atomic (overlapping the spin) instead of after the release; vmcnt(0) behind the spin still waits for it
# speedup vs baseline: 1.1591x; 1.0321x over previous
.LBB0_125:
	s_mov_b64 s[6:7], exec
	s_lshl_b32 s4, s13, 8
	v_mbcnt_lo_u32_b32 v2, s6, 0
	s_add_u32 s4, s10, s4
	v_mbcnt_hi_u32_b32 v2, s7, v2
	s_addc_u32 s5, s11, 0
	v_cmp_eq_u32_e32 vcc, 0, v2
	s_and_saveexec_b64 s[8:9], vcc
	s_cbranch_execz .LBB0_127
	s_bcnt1_i32_b64 s6, s[6:7]
	v_mov_b32_e32 v4, 0x1000
	v_mov_b32_e32 v5, s6
	global_atomic_add v4, v4, v5, s[4:5] offset:1024 sc0
	buffer_inv sc1

.LBB0_140:
	s_or_b64 exec, exec, s[8:9]
	s_waitcnt vmcnt(0)
	s_waitcnt vmcnt(0)

.LBB0_158:
	s_or_b64 exec, exec, s[6:7]
	s_mov_b64 s[6:7], exec
	v_mbcnt_lo_u32_b32 v1, s6, 0
	v_mbcnt_hi_u32_b32 v1, s7, v1
	v_cmp_eq_u32_e32 vcc, 0, v1
	s_waitcnt vmcnt(0)
	s_and_saveexec_b64 s[8:9], vcc
	s_cbranch_execz .LBB0_160
	s_bcnt1_i32_b64 s6, s[6:7]
	v_mov_b32_e32 v1, 0x2000
	v_mov_b32_e32 v2, s6
	global_atomic_add v1, v2, s[4:5] offset:1024

.LBB0_180:
	s_mov_b64 s[6:7], exec
	s_lshl_b32 s4, s56, 8
	v_mbcnt_lo_u32_b32 v1, s6, 0
	s_add_u32 s4, s10, s4
	v_mbcnt_hi_u32_b32 v1, s7, v1
	s_addc_u32 s5, s11, 0
	v_cmp_eq_u32_e32 vcc, 0, v1
	s_and_saveexec_b64 s[8:9], vcc
	s_cbranch_execz .LBB0_182
	s_bcnt1_i32_b64 s6, s[6:7]
	v_mov_b32_e32 v3, 0x1000
	v_mov_b32_e32 v4, s6
	global_atomic_add v3, v3, v4, s[4:5] offset:1024 sc0
	buffer_inv sc1

.LBB0_213:
	s_or_b64 exec, exec, s[6:7]
	s_mov_b64 s[6:7], exec
	v_mbcnt_lo_u32_b32 v0, s6, 0
	v_mbcnt_hi_u32_b32 v0, s7, v0
	v_cmp_eq_u32_e32 vcc, 0, v0
	s_waitcnt vmcnt(0)
	s_and_saveexec_b64 s[8:9], vcc
	s_cbranch_execz .LBB0_215
	s_bcnt1_i32_b64 s6, s[6:7]
	v_mov_b32_e32 v0, 0x2000
	v_mov_b32_e32 v1, s6
	global_atomic_add v0, v1, s[4:5] offset:1024

.LBB0_239:
	s_mov_b64 s[6:7], exec
	s_lshl_b32 s4, s52, 8
	v_mbcnt_lo_u32_b32 v1, s6, 0
	s_add_u32 s4, s10, s4
	v_mbcnt_hi_u32_b32 v1, s7, v1
	s_addc_u32 s5, s11, 0
	v_cmp_eq_u32_e32 vcc, 0, v1
	s_and_saveexec_b64 s[8:9], vcc
	s_cbranch_execz .LBB0_241
	s_bcnt1_i32_b64 s6, s[6:7]
	v_mov_b32_e32 v3, 0x1000
	v_mov_b32_e32 v4, s6
	global_atomic_add v3, v3, v4, s[4:5] offset:1024 sc0
	buffer_inv sc1

.LBB0_431:
	s_mov_b64 s[4:5], exec
	s_lshl_b32 s2, s8, 8
	v_readlane_b32 s6, v253, 1
	v_mbcnt_lo_u32_b32 v0, s4, 0
	v_readlane_b32 s7, v253, 2
	s_add_u32 s2, s6, s2
	v_mbcnt_hi_u32_b32 v0, s5, v0
	s_addc_u32 s3, s7, 0
	v_cmp_eq_u32_e32 vcc, 0, v0
	s_and_saveexec_b64 s[6:7], vcc
	s_cbranch_execz .LBB0_433
	s_bcnt1_i32_b64 s4, s[4:5]
	v_mov_b32_e32 v4, s4
	v_mov_b32_e32 v5, 0x1000
	global_atomic_add v4, v5, v4, s[2:3] offset:1024 sc0
	buffer_inv sc1

.LBB0_446:
	s_or_b64 exec, exec, s[6:7]
	s_waitcnt vmcnt(0)
	s_waitcnt vmcnt(0)

.LBB0_464:
	s_or_b64 exec, exec, s[4:5]
	s_mov_b64 s[4:5], exec
	v_mbcnt_lo_u32_b32 v0, s4, 0
	v_mbcnt_hi_u32_b32 v0, s5, v0
	v_cmp_eq_u32_e32 vcc, 0, v0
	s_waitcnt vmcnt(0)
	s_and_saveexec_b64 s[6:7], vcc
	s_cbranch_execz .LBB0_466
	s_bcnt1_i32_b64 s4, s[4:5]
	v_mov_b32_e32 v0, s4
	v_mov_b32_e32 v2, 0x2000
	global_atomic_add v2, v0, s[2:3] offset:1024

.LBB0_658:
	s_mov_b64 s[6:7], exec
	s_lshl_b32 s4, s10, 8
	v_readlane_b32 s8, v253, 1
	v_mbcnt_lo_u32_b32 v0, s6, 0
	v_readlane_b32 s9, v253, 2
	s_add_u32 s4, s8, s4
	v_mbcnt_hi_u32_b32 v0, s7, v0
	s_addc_u32 s5, s9, 0
	v_cmp_eq_u32_e32 vcc, 0, v0
	s_and_saveexec_b64 s[8:9], vcc
	s_cbranch_execz .LBB0_660
	s_bcnt1_i32_b64 s6, s[6:7]
	v_mov_b32_e32 v4, s6
	v_mov_b32_e32 v5, 0x1000
	global_atomic_add v4, v5, v4, s[4:5] offset:1024 sc0
	buffer_inv sc1

.Lbar_local_g2:
	s_mov_b64 s[6:7], exec
	v_mbcnt_lo_u32_b32 v0, s6, 0
	v_mbcnt_hi_u32_b32 v0, s7, v0
	v_cmp_eq_u32_e32 vcc, 0, v0
	s_waitcnt vmcnt(0)
	s_and_saveexec_b64 s[8:9], vcc
	s_cbranch_execz .LBB0_693
	s_bcnt1_i32_b64 s6, s[6:7]
	v_mov_b32_e32 v0, s6
	v_mov_b32_e32 v2, 0x2000
	global_atomic_add v2, v0, s[4:5] offset:1024

.Lbar_local_peer:
	s_mov_b64 s[4:5], exec
	v_mbcnt_lo_u32_b32 v0, s4, 0
	v_mbcnt_hi_u32_b32 v0, s5, v0
	v_cmp_eq_u32_e32 vcc, 0, v0
	s_waitcnt vmcnt(0)
	s_and_saveexec_b64 s[6:7], vcc
	s_cbranch_execz .LBB0_292
	s_bcnt1_i32_b64 s4, s[4:5]
	v_mov_b32_e32 v0, s4
	v_mov_b32_e32 v2, 0x2000
	global_atomic_add v2, v0, s[2:3] offset:1024
	s_branch .LBB0_292
